# adds: ret_kv and ret_out tile loads issued as batches (one or two latencies per unit instead of 8-16)
# baseline (speedup 1.0000x reference)
; #define LAS __attribute__((address_space(3)))
; __device__ __forceinline__ bf16_t f2bf(float f) { return (bf16_t)(pk_bf16(f, 0.f) & 0xffffu); }
; __device__ __forceinline__ void ret_out_unit(int b, int h, int c, LAS unsigned char* lds, const bf16_t* PROJ, const float* KV, bf16_t* H, int tid) {
;     ...
;     for (int r = 0; r < 4; ++r) { const int idx = tid + 512 * r, tok = idx & 127, seg = idx >> 7;
;         const bf16_t* rp = PROJ + (R0 + tok) * EIN + h * 128 + seg * 8;
;         const u32x4 kv = *(const u32x4*)(rp + 1024), vv = *(const u32x4*)(rp + 2048);
;         *(LAS u32x4*)(Ks + tok * 272 + seg * 16) = kv;
; #pragma unroll
;         for (int i = 0; i < 4; ++i) {
;             *(LAS bf16_t*)(VT + (seg * 8 + 2 * i) * 272 + tok * 2) = (bf16_t)(vv[i] & 0xffffu);
;             *(LAS bf16_t*)(VT + (seg * 8 + 2 * i + 1) * 272 + tok * 2) = (bf16_t)(vv[i] >> 16); } }
;     const float* Sp = KV + ((size_t)((b * 8 + h) * 32 + c)) * 16384;
; #pragma unroll
;     for (int r = 0; r < 8; ++r) { const int idx = tid + 512 * r, d = idx & 127, es = idx >> 7;
;         const f32x4 s4 = *(const f32x4*)(Sp + (size_t)d * 128 + 4 * es);
; #pragma unroll
;         for (int i = 0; i < 4; ++i) *(LAS bf16_t*)(ST + (4 * es + i) * 272 + d * 2) = f2bf(s4[i]); }
.LBB0_418:
	s_bfe_u32 s22, s3, 0x30005
	v_cvt_f32_ubyte0_e32 v0, s22
	v_sub_f32_e32 v0, 0xc0a00000, v0
	v_cmp_gt_f32_e32 vcc, s34, v0
	s_and_b32 s13, s3, 31
	s_ashr_i32 s18, s3, 8
	v_cndmask_b32_e32 v1, 0, v168, vcc
	v_add_f32_e32 v0, v0, v1
	v_exp_f32_e32 v0, v0
	s_and_b64 s[20:21], vcc, exec
	s_cselect_b32 s19, 0xffffffc0, 0
	s_lshl_b32 s20, s13, 7
	v_ldexp_f32 v0, v0, s19
	s_ashr_i32 s19, s18, 31
	s_lshl_b64 s[18:19], s[18:19], 12
	s_or_b32 s18, s18, s20
	v_sub_f32_e32 v16, 1.0, v0
	v_or_b32_e32 v0, s18, v80
	v_mov_b64_e32 v[4:5], s[16:17]
	v_mad_u64_u32 v[0:1], s[20:21], v0, s35, v[4:5]
	v_mad_i32_i24 v1, s19, v169, v1
	s_lshl_b32 s24, s22, 8
	v_lshl_add_u64 v[6:7], v[0:1], 0, s[24:25]
	v_lshl_add_u64 v[8:9], v[82:83], 1, v[6:7]
	v_lshl_add_u64 v[0:1], v[82:83], 1, v[6:7]
	global_load_dwordx4 v[220:223], v[0:1], off offset:2048
	v_add_co_u32_e32 v0, vcc, s33, v0
	s_nop 1
	v_addc_co_u32_e32 v1, vcc, 0, v1, vcc
	global_load_dwordx4 v[224:227], v[0:1], off
	v_lshl_add_u64 v[0:1], v[84:85], 1, v[6:7]
	global_load_dwordx4 v[228:231], v[0:1], off offset:2048
	v_add_co_u32_e32 v0, vcc, s33, v0
	s_nop 1
	v_addc_co_u32_e32 v1, vcc, 0, v1, vcc
	global_load_dwordx4 v[232:235], v[0:1], off
	v_lshl_add_u64 v[0:1], v[86:87], 1, v[6:7]
	global_load_dwordx4 v[236:239], v[0:1], off offset:2048
	v_add_co_u32_e32 v0, vcc, s33, v0
	s_nop 1
	v_addc_co_u32_e32 v1, vcc, 0, v1, vcc
	global_load_dwordx4 v[240:243], v[0:1], off
	v_lshl_add_u64 v[0:1], v[88:89], 1, v[6:7]
	global_load_dwordx4 v[244:247], v[0:1], off offset:2048
	v_add_co_u32_e32 v0, vcc, s33, v0
	s_nop 1
	v_addc_co_u32_e32 v1, vcc, 0, v1, vcc
	global_load_dwordx4 v[248:251], v[0:1], off
	s_waitcnt vmcnt(0)
	v_mov_b64_e32 v[0:1], v[220:221]
	v_mov_b64_e32 v[2:3], v[222:223]
	s_and_b32 s20, s3, 0xffffff00
	s_lshl_b32 s21, s22, 5
	s_or_b32 s20, s21, s20
	s_or_b32 s20, s20, s13
	s_ashr_i32 s21, s20, 31
	s_lshl_b64 s[20:21], s[20:21], 16
	v_lshl_add_u64 v[114:115], s[18:19], 0, v[108:109]
	v_lshlrev_b32_e32 v128, 1, v110
	v_add_u32_e32 v24, v111, v110
	s_waitcnt vmcnt(0)
	ds_write_b128 v160, v[0:3]
	v_add_co_u32_e32 v0, vcc, s33, v8
	s_nop 1
	v_addc_co_u32_e32 v1, vcc, 0, v9, vcc
	v_mov_b64_e32 v[0:1], v[224:225]
	v_mov_b64_e32 v[2:3], v[226:227]
	v_lshl_add_u64 v[8:9], v[84:85], 1, v[6:7]
	s_waitcnt vmcnt(0)
	ds_write_b16 v161, v0 offset:34816
	ds_write_b16_d16_hi v161, v0 offset:35088
	ds_write_b16 v161, v1 offset:35360
	ds_write_b16_d16_hi v161, v1 offset:35632
	ds_write_b16 v161, v2 offset:35904
	ds_write_b16_d16_hi v161, v2 offset:36176
	ds_write_b16 v161, v3 offset:36448
	ds_write_b16_d16_hi v161, v3 offset:36720
	v_mov_b64_e32 v[0:1], v[228:229]
	v_mov_b64_e32 v[2:3], v[230:231]
	s_waitcnt vmcnt(0)
	ds_write_b128 v180, v[0:3]
	v_add_co_u32_e32 v0, vcc, s33, v8
	s_nop 1
	v_addc_co_u32_e32 v1, vcc, 0, v9, vcc
	v_mov_b64_e32 v[0:1], v[232:233]
	v_mov_b64_e32 v[2:3], v[234:235]
	v_lshl_add_u64 v[8:9], v[86:87], 1, v[6:7]
	v_lshl_add_u64 v[6:7], v[88:89], 1, v[6:7]
	s_waitcnt vmcnt(0)
	ds_write_b16 v181, v0 offset:34816
	ds_write_b16_d16_hi v181, v0 offset:35088
	ds_write_b16 v181, v1 offset:35360
	ds_write_b16_d16_hi v181, v1 offset:35632
	ds_write_b16 v181, v2 offset:35904
	ds_write_b16_d16_hi v181, v2 offset:36176
	ds_write_b16 v181, v3 offset:36448
	ds_write_b16_d16_hi v181, v3 offset:36720
	v_mov_b64_e32 v[0:1], v[236:237]
	v_mov_b64_e32 v[2:3], v[238:239]
	s_waitcnt vmcnt(0)
	ds_write_b128 v182, v[0:3]
	v_add_co_u32_e32 v0, vcc, s33, v8
	s_nop 1
	v_addc_co_u32_e32 v1, vcc, 0, v9, vcc
	v_mov_b64_e32 v[0:1], v[240:241]
	v_mov_b64_e32 v[2:3], v[242:243]
	s_waitcnt vmcnt(0)
	ds_write_b16 v183, v0 offset:34816
	ds_write_b16_d16_hi v183, v0 offset:35088
	ds_write_b16 v183, v1 offset:35360
	ds_write_b16_d16_hi v183, v1 offset:35632
	ds_write_b16 v183, v2 offset:35904
	ds_write_b16_d16_hi v183, v2 offset:36176
	ds_write_b16 v183, v3 offset:36448
	ds_write_b16_d16_hi v183, v3 offset:36720
	v_mov_b64_e32 v[0:1], v[244:245]
	v_mov_b64_e32 v[2:3], v[246:247]
	s_waitcnt vmcnt(0)
	ds_write_b128 v184, v[0:3]
	v_add_co_u32_e32 v0, vcc, s33, v6
	s_nop 1
	v_addc_co_u32_e32 v1, vcc, 0, v7, vcc
	v_mov_b64_e32 v[0:1], v[248:249]
	v_mov_b64_e32 v[2:3], v[250:251]
	v_lshl_add_u64 v[6:7], v[90:91], 0, s[20:21]
	v_cmp_gt_f32_e32 vcc, s23, v16
	s_and_b64 s[18:19], vcc, exec
	s_cselect_b32 s13, 32, 0
	v_ldexp_f32 v16, v16, s13
	v_log_f32_e32 v16, v16
	v_cndmask_b32_e32 v17, 0, v170, vcc
	s_waitcnt vmcnt(0)
	ds_write_b16 v185, v0 offset:34816
	ds_write_b16_d16_hi v185, v0 offset:35088
	ds_write_b16 v185, v1 offset:35360
	ds_write_b16_d16_hi v185, v1 offset:35632
	ds_write_b16 v185, v2 offset:35904
	ds_write_b16_d16_hi v185, v2 offset:36176
	ds_write_b16 v185, v3 offset:36448
	ds_write_b16_d16_hi v185, v3 offset:36720
	v_lshl_add_u64 v[0:1], v[92:93], 2, v[6:7]
	global_load_dwordx4 v[220:223], v[0:1], off
	v_lshl_add_u64 v[0:1], v[94:95], 2, v[6:7]
	global_load_dwordx4 v[224:227], v[0:1], off
	v_lshl_add_u64 v[0:1], v[96:97], 2, v[6:7]
	global_load_dwordx4 v[228:231], v[0:1], off
	v_lshl_add_u64 v[0:1], v[98:99], 2, v[6:7]
	global_load_dwordx4 v[232:235], v[0:1], off
	v_lshl_add_u64 v[0:1], v[100:101], 2, v[6:7]
	global_load_dwordx4 v[236:239], v[0:1], off
	v_lshl_add_u64 v[0:1], v[102:103], 2, v[6:7]
	global_load_dwordx4 v[240:243], v[0:1], off
	v_lshl_add_u64 v[0:1], v[104:105], 2, v[6:7]
	global_load_dwordx4 v[244:247], v[0:1], off
	v_lshl_add_u64 v[0:1], v[106:107], 2, v[6:7]
	global_load_dwordx4 v[248:251], v[0:1], off
	s_waitcnt vmcnt(0)
	v_lshl_add_u64 v[0:1], v[92:93], 2, v[6:7]
	v_mov_b64_e32 v[0:1], v[220:221]
	v_mov_b64_e32 v[2:3], v[222:223]
	s_waitcnt vmcnt(0)
; #define LAS __attribute__((address_space(3)))
; __device__ __forceinline__ unsigned pk_bf16(float lo, float hi) { unsigned r; asm volatile("v_cvt_pk_bf16_f32 %0, %1, %2" : "=v"(r) : "v"(lo), "v"(hi)); return r; }
; __device__ __forceinline__ bf16_t f2bf(float f) { return (bf16_t)(pk_bf16(f, 0.f) & 0xffffu); }
; __device__ __forceinline__ f32x4 mfma16(bf16x8 a, bf16x8 b, f32x4 c) { return __builtin_amdgcn_mfma_f32_16x16x32_bf16(a, b, c, 0, 0, 0); }
; __device__ __forceinline__ void ret_out_unit(int b, int h, int c, LAS unsigned char* lds, const bf16_t* PROJ, const float* KV, bf16_t* H, int tid) {
;     ...
;     for (int r = 0; r < 8; ++r) { const int idx = tid + 512 * r, d = idx & 127, es = idx >> 7;
;         const f32x4 s4 = *(const f32x4*)(Sp + (size_t)d * 128 + 4 * es);
; #pragma unroll
;         for (int i = 0; i < 4; ++i) *(LAS bf16_t*)(ST + (4 * es + i) * 272 + d * 2) = f2bf(s4[i]); }
;     __syncthreads();
;     const int i = 16 * wave + fr;
;     const size_t qrow = R0 + i;
;     bf16x8 qf[4];
; #pragma unroll
;     for (int kk = 0; kk < 4; ++kk) qf[kk] = *(const bf16x8*)(PROJ + qrow * EIN + h * 128 + 32 * kk + 8 * fq);
; #pragma unroll
;     for (int cb = 0; cb < 8; ++cb) { f32x4 acc = {0.f, 0.f, 0.f, 0.f};
; #pragma unroll
;         for (int kk = 0; kk < 4; ++kk) { const bf16x8 kf = *(const LAS bf16x8*)(Ks + (16 * cb + fr) * 272 + (32 * kk + 8 * fq) * 2); acc = mfma16(kf, qf[kk], acc); }
;         float v[4];
; #pragma unroll
;         for (int t = 0; t < 4; ++t) { const int dl = i - (16 * cb + 4 * fq + t); v[t] = dl >= 0 ? acc[t] * 0.08838834764831845f * exp2f(lg2 * (float)dl) : 0.f; }
;         u32x2 w; w.x = pk_bf16(v[0], v[1]); w.y = pk_bf16(v[2], v[3]);
;         *(LAS u32x2*)(SC + i * 272 + (16 * cb + 4 * fq) * 2) = w; }
	v_cvt_pk_bf16_f32 v0, v0, v129
	ds_write_b16 v186, v0
	v_cvt_pk_bf16_f32 v0, v1, v129
	ds_write_b16 v186, v0 offset:272
	v_cvt_pk_bf16_f32 v0, v2, v129
	ds_write_b16 v186, v0 offset:544
	v_cvt_pk_bf16_f32 v0, v3, v129
	ds_write_b16 v187, v0
	v_lshl_add_u64 v[0:1], v[94:95], 2, v[6:7]
	v_mov_b64_e32 v[0:1], v[224:225]
	v_mov_b64_e32 v[2:3], v[226:227]
	s_waitcnt vmcnt(0)
	v_cvt_pk_bf16_f32 v0, v0, v129
	ds_write_b16 v188, v0
	v_cvt_pk_bf16_f32 v0, v1, v129
	ds_write_b16 v188, v0 offset:272
	v_cvt_pk_bf16_f32 v0, v2, v129
	ds_write_b16 v188, v0 offset:544
	v_cvt_pk_bf16_f32 v0, v3, v129
	ds_write_b16 v189, v0
	v_lshl_add_u64 v[0:1], v[96:97], 2, v[6:7]
	v_mov_b64_e32 v[0:1], v[228:229]
	v_mov_b64_e32 v[2:3], v[230:231]
	s_waitcnt vmcnt(0)
	v_cvt_pk_bf16_f32 v0, v0, v129
	ds_write_b16 v190, v0
	v_cvt_pk_bf16_f32 v0, v1, v129
	ds_write_b16 v190, v0 offset:272
	v_cvt_pk_bf16_f32 v0, v2, v129
	ds_write_b16 v190, v0 offset:544
	v_cvt_pk_bf16_f32 v0, v3, v129
	ds_write_b16 v191, v0
	v_lshl_add_u64 v[0:1], v[98:99], 2, v[6:7]
	v_mov_b64_e32 v[0:1], v[232:233]
	v_mov_b64_e32 v[2:3], v[234:235]
	s_waitcnt vmcnt(0)
	v_cvt_pk_bf16_f32 v0, v0, v129
	ds_write_b16 v192, v0
	v_cvt_pk_bf16_f32 v0, v1, v129
	ds_write_b16 v192, v0 offset:272
	v_cvt_pk_bf16_f32 v0, v2, v129
	ds_write_b16 v192, v0 offset:544
	v_cvt_pk_bf16_f32 v0, v3, v129
	ds_write_b16 v193, v0
	v_lshl_add_u64 v[0:1], v[100:101], 2, v[6:7]
	v_mov_b64_e32 v[0:1], v[236:237]
	v_mov_b64_e32 v[2:3], v[238:239]
	s_waitcnt vmcnt(0)
	v_cvt_pk_bf16_f32 v0, v0, v129
	ds_write_b16 v194, v0
	v_cvt_pk_bf16_f32 v0, v1, v129
	ds_write_b16 v194, v0 offset:272
	v_cvt_pk_bf16_f32 v0, v2, v129
	ds_write_b16 v194, v0 offset:544
	v_cvt_pk_bf16_f32 v0, v3, v129
	ds_write_b16 v195, v0
	v_lshl_add_u64 v[0:1], v[102:103], 2, v[6:7]
	v_mov_b64_e32 v[0:1], v[240:241]
	v_mov_b64_e32 v[2:3], v[242:243]
	s_waitcnt vmcnt(0)
	v_cvt_pk_bf16_f32 v0, v0, v129
	ds_write_b16 v196, v0
	v_cvt_pk_bf16_f32 v0, v1, v129
	ds_write_b16 v196, v0 offset:272
	v_cvt_pk_bf16_f32 v0, v2, v129
	ds_write_b16 v196, v0 offset:544
	v_cvt_pk_bf16_f32 v0, v3, v129
	ds_write_b16 v197, v0
	v_lshl_add_u64 v[0:1], v[104:105], 2, v[6:7]
	v_mov_b64_e32 v[0:1], v[244:245]
	v_mov_b64_e32 v[2:3], v[246:247]
	s_waitcnt vmcnt(0)
	v_cvt_pk_bf16_f32 v0, v0, v129
	ds_write_b16 v198, v0
	v_cvt_pk_bf16_f32 v0, v1, v129
	ds_write_b16 v198, v0 offset:272
	v_cvt_pk_bf16_f32 v0, v2, v129
	ds_write_b16 v198, v0 offset:544
	v_cvt_pk_bf16_f32 v0, v3, v129
	ds_write_b16 v199, v0
	v_lshl_add_u64 v[0:1], v[106:107], 2, v[6:7]
	v_mov_b64_e32 v[0:1], v[248:249]
	v_mov_b64_e32 v[2:3], v[250:251]
	s_waitcnt vmcnt(0)
	v_cvt_pk_bf16_f32 v0, v0, v129
	ds_write_b16 v200, v0
	v_cvt_pk_bf16_f32 v0, v1, v129
	ds_write_b16 v200, v0 offset:272
	v_cvt_pk_bf16_f32 v0, v2, v129
	ds_write_b16 v200, v0 offset:544
	v_cvt_pk_bf16_f32 v0, v3, v129
	ds_write_b16 v201, v0
	v_mad_u64_u32 v[0:1], s[18:19], v114, s35, v[4:5]
	v_mad_i32_i24 v1, v115, s35, v1
	v_lshl_add_u64 v[116:117], v[0:1], 0, s[24:25]
	v_lshl_add_u64 v[0:1], v[116:117], 0, v[128:129]
	s_waitcnt lgkmcnt(0)
	s_barrier
	global_load_dwordx4 v[12:15], v[0:1], off
	global_load_dwordx4 v[8:11], v[0:1], off offset:64
	global_load_dwordx4 v[4:7], v[0:1], off offset:128
	s_nop 0
	global_load_dwordx4 v[0:3], v[0:1], off offset:192
	v_sub_f32_e32 v113, v16, v17
	ds_read_b128 v[16:19], v118
	ds_read_b128 v[20:23], v118 offset:64
	v_add_u32_e32 v128, v111, v81
	s_add_u32 s18, s6, s24
	s_addc_u32 s19, s7, 0
	s_add_i32 s3, s3, s2
	s_cmpk_gt_i32 s3, 0x1ff
	s_waitcnt vmcnt(3) lgkmcnt(1)
	v_mfma_f32_16x16x32_bf16 v[16:19], v[16:19], v[12:15], 0
	s_waitcnt vmcnt(2) lgkmcnt(0)
	v_mfma_f32_16x16x32_bf16 v[16:19], v[20:23], v[8:11], v[16:19]
	ds_read_b128 v[20:23], v118 offset:128
	s_waitcnt vmcnt(1) lgkmcnt(0)
	v_mfma_f32_16x16x32_bf16 v[16:19], v[20:23], v[4:7], v[16:19]
	ds_read_b128 v[20:23], v118 offset:192
	s_waitcnt vmcnt(0) lgkmcnt(0)
	v_mfma_f32_16x16x32_bf16 v[16:19], v[20:23], v[0:3], v[16:19]
	v_mul_f32_e32 v20, v113, v119
	v_cmp_gt_f32_e32 vcc, s34, v20
	s_nop 5
	v_mul_f32_e32 v16, 0x3db504f3, v16
	v_cndmask_b32_e32 v20, 0, v168, vcc
	v_fmac_f32_e32 v20, v113, v119
	v_exp_f32_e32 v20, v20
	v_cndmask_b32_e32 v21, 0, v171, vcc
	v_mul_f32_e32 v17, 0x3db504f3, v17
	v_mul_f32_e32 v18, 0x3db504f3, v18
	v_ldexp_f32 v20, v20, v21
	v_mul_f32_e32 v16, v20, v16
	v_mul_f32_e32 v20, v113, v120
	v_cmp_gt_f32_e32 vcc, s34, v20
	v_mul_f32_e32 v19, 0x3db504f3, v19
	v_cndmask_b32_e64 v16, 0, v16, s[38:39]
	v_cndmask_b32_e32 v20, 0, v168, vcc
	v_fmac_f32_e32 v20, v113, v120
	v_exp_f32_e32 v20, v20
	v_cndmask_b32_e32 v21, 0, v171, vcc
	v_ldexp_f32 v20, v20, v21
	v_mul_f32_e32 v17, v20, v17
	v_mul_f32_e32 v20, v113, v121
	v_cmp_gt_f32_e32 vcc, s34, v20
	v_cndmask_b32_e64 v17, 0, v17, s[40:41]
	v_cvt_pk_bf16_f32 v16, v16, v17
	s_nop 0
	v_cndmask_b32_e32 v20, 0, v168, vcc
	v_fmac_f32_e32 v20, v113, v121
	v_exp_f32_e32 v20, v20
	v_cndmask_b32_e32 v21, 0, v171, vcc
	v_ldexp_f32 v20, v20, v21
	v_mul_f32_e32 v18, v20, v18
	v_mul_f32_e32 v20, v113, v122
	v_cmp_gt_f32_e32 vcc, s34, v20
	v_cndmask_b32_e64 v18, 0, v18, s[42:43]
	s_nop 0
	v_cndmask_b32_e32 v20, 0, v168, vcc
	v_fmac_f32_e32 v20, v113, v122
	v_exp_f32_e32 v20, v20
	v_cndmask_b32_e32 v21, 0, v171, vcc
	v_ldexp_f32 v20, v20, v21
	v_mul_f32_e32 v19, v20, v19
	v_cndmask_b32_e64 v19, 0, v19, s[44:45]
	v_cvt_pk_bf16_f32 v17, v18, v19
	ds_write_b64 v24, v[16:17]
	ds_read_b128 v[16:19], v118 offset:4352
	ds_read_b128 v[20:23], v118 offset:4416
	s_waitcnt lgkmcnt(1)
	v_mfma_f32_16x16x32_bf16 v[16:19], v[16:19], v[12:15], 0
	s_waitcnt lgkmcnt(0)
	v_mfma_f32_16x16x32_bf16 v[16:19], v[20:23], v[8:11], v[16:19]
	ds_read_b128 v[20:23], v118 offset:4480
	s_waitcnt lgkmcnt(0)
; #define LAS __attribute__((address_space(3)))
; __device__ __forceinline__ unsigned pk_bf16(float lo, float hi) { unsigned r; asm volatile("v_cvt_pk_bf16_f32 %0, %1, %2" : "=v"(r) : "v"(lo), "v"(hi)); return r; }
; __device__ __forceinline__ f32x4 mfma16(bf16x8 a, bf16x8 b, f32x4 c) { return __builtin_amdgcn_mfma_f32_16x16x32_bf16(a, b, c, 0, 0, 0); }
; __device__ __forceinline__ void ret_out_unit(int b, int h, int c, LAS unsigned char* lds, const bf16_t* PROJ, const float* KV, bf16_t* H, int tid) {
;     ...
;     for (int cb = 0; cb < 8; ++cb) { f32x4 acc = {0.f, 0.f, 0.f, 0.f};
; #pragma unroll
;         for (int kk = 0; kk < 4; ++kk) { const bf16x8 kf = *(const LAS bf16x8*)(Ks + (16 * cb + fr) * 272 + (32 * kk + 8 * fq) * 2); acc = mfma16(kf, qf[kk], acc); }
;         float v[4];
; #pragma unroll
;         for (int t = 0; t < 4; ++t) { const int dl = i - (16 * cb + 4 * fq + t); v[t] = dl >= 0 ? acc[t] * 0.08838834764831845f * exp2f(lg2 * (float)dl) : 0.f; }
;         u32x2 w; w.x = pk_bf16(v[0], v[1]); w.y = pk_bf16(v[2], v[3]);
;         *(LAS u32x2*)(SC + i * 272 + (16 * cb + 4 * fq) * 2) = w; }
	v_mfma_f32_16x16x32_bf16 v[16:19], v[20:23], v[4:7], v[16:19]
	ds_read_b128 v[20:23], v118 offset:4544
	s_waitcnt lgkmcnt(0)
	v_mfma_f32_16x16x32_bf16 v[16:19], v[20:23], v[0:3], v[16:19]
	v_mul_f32_e32 v20, v113, v123
	v_cmp_gt_f32_e32 vcc, s34, v20
	s_nop 5
	v_mul_f32_e32 v16, 0x3db504f3, v16
	v_cndmask_b32_e32 v20, 0, v168, vcc
	v_fmac_f32_e32 v20, v113, v123
	v_exp_f32_e32 v20, v20
	v_cndmask_b32_e32 v21, 0, v171, vcc
	v_mul_f32_e32 v17, 0x3db504f3, v17
	v_mul_f32_e32 v18, 0x3db504f3, v18
	v_ldexp_f32 v20, v20, v21
	v_mul_f32_e32 v16, v20, v16
	v_mul_f32_e32 v20, v113, v124
	v_cmp_gt_f32_e32 vcc, s34, v20
	v_mul_f32_e32 v19, 0x3db504f3, v19
	v_cndmask_b32_e64 v16, 0, v16, s[46:47]
	v_cndmask_b32_e32 v20, 0, v168, vcc
	v_fmac_f32_e32 v20, v113, v124
	v_exp_f32_e32 v20, v20
	v_cndmask_b32_e32 v21, 0, v171, vcc
	v_ldexp_f32 v20, v20, v21
	v_mul_f32_e32 v17, v20, v17
	v_mul_f32_e32 v20, v113, v125
	v_cmp_gt_f32_e32 vcc, s34, v20
	v_cndmask_b32_e64 v17, 0, v17, s[48:49]
	v_cvt_pk_bf16_f32 v16, v16, v17
	s_nop 0
	v_cndmask_b32_e32 v20, 0, v168, vcc
	v_fmac_f32_e32 v20, v113, v125
	v_exp_f32_e32 v20, v20
	v_cndmask_b32_e32 v21, 0, v171, vcc
	v_ldexp_f32 v20, v20, v21
	v_mul_f32_e32 v18, v20, v18
	v_mul_f32_e32 v20, v113, v126
	v_cmp_gt_f32_e32 vcc, s34, v20
	v_cndmask_b32_e64 v18, 0, v18, s[50:51]
	s_nop 0
	v_cndmask_b32_e32 v20, 0, v168, vcc
	v_fmac_f32_e32 v20, v113, v126
	v_exp_f32_e32 v20, v20
	v_cndmask_b32_e32 v21, 0, v171, vcc
	v_ldexp_f32 v20, v20, v21
	v_mul_f32_e32 v19, v20, v19
	v_cndmask_b32_e64 v19, 0, v19, s[52:53]
	v_cvt_pk_bf16_f32 v17, v18, v19
	ds_write_b64 v24, v[16:17] offset:32
	ds_read_b128 v[16:19], v118 offset:8704
	ds_read_b128 v[20:23], v118 offset:8768
	s_waitcnt lgkmcnt(1)
	v_mfma_f32_16x16x32_bf16 v[16:19], v[16:19], v[12:15], 0
	s_waitcnt lgkmcnt(0)
	v_mfma_f32_16x16x32_bf16 v[16:19], v[20:23], v[8:11], v[16:19]
	ds_read_b128 v[20:23], v118 offset:8832
	s_waitcnt lgkmcnt(0)
	v_mfma_f32_16x16x32_bf16 v[16:19], v[20:23], v[4:7], v[16:19]
	ds_read_b128 v[20:23], v118 offset:8896
	s_waitcnt lgkmcnt(0)
	v_mfma_f32_16x16x32_bf16 v[16:19], v[20:23], v[0:3], v[16:19]
	v_mul_f32_e32 v20, v113, v127
	v_cmp_gt_f32_e32 vcc, s34, v20
	s_nop 5
	v_mul_f32_e32 v16, 0x3db504f3, v16
	v_cndmask_b32_e32 v20, 0, v168, vcc
	v_fmac_f32_e32 v20, v113, v127
	v_exp_f32_e32 v20, v20
	v_cndmask_b32_e32 v21, 0, v171, vcc
	v_mul_f32_e32 v17, 0x3db504f3, v17
	v_mul_f32_e32 v18, 0x3db504f3, v18
	v_ldexp_f32 v20, v20, v21
	v_mul_f32_e32 v16, v20, v16
	v_mul_f32_e32 v20, v113, v130
	v_cmp_gt_f32_e32 vcc, s34, v20
	v_mul_f32_e32 v19, 0x3db504f3, v19
	v_cndmask_b32_e64 v16, 0, v16, s[54:55]
	v_cndmask_b32_e32 v20, 0, v168, vcc
	v_fmac_f32_e32 v20, v113, v130
	v_exp_f32_e32 v20, v20
	v_cndmask_b32_e32 v21, 0, v171, vcc
	v_ldexp_f32 v20, v20, v21
	v_mul_f32_e32 v17, v20, v17
	v_mul_f32_e32 v20, v113, v133
	v_cmp_gt_f32_e32 vcc, s34, v20
	v_cndmask_b32_e64 v17, 0, v17, s[56:57]
	v_cvt_pk_bf16_f32 v16, v16, v17
	s_nop 0
	v_cndmask_b32_e32 v20, 0, v168, vcc
	v_fmac_f32_e32 v20, v113, v133
	v_exp_f32_e32 v20, v20
	v_cndmask_b32_e32 v21, 0, v171, vcc
	v_ldexp_f32 v20, v20, v21
	v_mul_f32_e32 v18, v20, v18
	v_mul_f32_e32 v20, v113, v134
	v_cmp_gt_f32_e32 vcc, s34, v20
	v_cndmask_b32_e64 v18, 0, v18, s[58:59]
	s_nop 0
	v_cndmask_b32_e32 v20, 0, v168, vcc
	v_fmac_f32_e32 v20, v113, v134
	v_exp_f32_e32 v20, v20
	v_cndmask_b32_e32 v21, 0, v171, vcc
	v_ldexp_f32 v20, v20, v21
	v_mul_f32_e32 v19, v20, v19
	v_cndmask_b32_e64 v19, 0, v19, s[60:61]
	v_cvt_pk_bf16_f32 v17, v18, v19
	ds_write_b64 v24, v[16:17] offset:64
	ds_read_b128 v[16:19], v118 offset:13056
	ds_read_b128 v[20:23], v118 offset:13120
	s_waitcnt lgkmcnt(1)
	v_mfma_f32_16x16x32_bf16 v[16:19], v[16:19], v[12:15], 0
	s_waitcnt lgkmcnt(0)
	v_mfma_f32_16x16x32_bf16 v[16:19], v[20:23], v[8:11], v[16:19]
	ds_read_b128 v[20:23], v118 offset:13184
	s_waitcnt lgkmcnt(0)
	v_mfma_f32_16x16x32_bf16 v[16:19], v[20:23], v[4:7], v[16:19]
	ds_read_b128 v[20:23], v118 offset:13248
	s_waitcnt lgkmcnt(0)
	v_mfma_f32_16x16x32_bf16 v[16:19], v[20:23], v[0:3], v[16:19]
	v_mul_f32_e32 v20, v113, v135
	v_cmp_gt_f32_e32 vcc, s34, v20
	s_nop 5
	v_mul_f32_e32 v16, 0x3db504f3, v16
	v_cndmask_b32_e32 v20, 0, v168, vcc
	v_fmac_f32_e32 v20, v113, v135
	v_exp_f32_e32 v20, v20
	v_cndmask_b32_e32 v21, 0, v171, vcc
	v_mul_f32_e32 v17, 0x3db504f3, v17
	v_mul_f32_e32 v18, 0x3db504f3, v18
	v_ldexp_f32 v20, v20, v21
	v_mul_f32_e32 v16, v20, v16
	v_mul_f32_e32 v20, v113, v136
	v_cmp_gt_f32_e32 vcc, s34, v20
	v_mul_f32_e32 v19, 0x3db504f3, v19
	v_cndmask_b32_e64 v16, 0, v16, s[62:63]
	v_cndmask_b32_e32 v20, 0, v168, vcc
	v_fmac_f32_e32 v20, v113, v136
	v_exp_f32_e32 v20, v20
	v_cndmask_b32_e32 v21, 0, v171, vcc
	v_ldexp_f32 v20, v20, v21
	v_mul_f32_e32 v17, v20, v17
	v_mul_f32_e32 v20, v113, v137
	v_cmp_gt_f32_e32 vcc, s34, v20
	v_cndmask_b32_e64 v17, 0, v17, s[64:65]
	v_cvt_pk_bf16_f32 v16, v16, v17
	s_nop 0
	v_cndmask_b32_e32 v20, 0, v168, vcc
	v_fmac_f32_e32 v20, v113, v137
	v_exp_f32_e32 v20, v20
	v_cndmask_b32_e32 v21, 0, v171, vcc
	v_ldexp_f32 v20, v20, v21
	v_mul_f32_e32 v18, v20, v18
	v_mul_f32_e32 v20, v113, v138
	v_cmp_gt_f32_e32 vcc, s34, v20
	v_cndmask_b32_e64 v18, 0, v18, s[66:67]
	s_nop 0
	v_cndmask_b32_e32 v20, 0, v168, vcc
	v_fmac_f32_e32 v20, v113, v138
	v_exp_f32_e32 v20, v20
	v_cndmask_b32_e32 v21, 0, v171, vcc
	v_ldexp_f32 v20, v20, v21
	v_mul_f32_e32 v19, v20, v19
	v_cndmask_b32_e64 v19, 0, v19, s[68:69]
	v_cvt_pk_bf16_f32 v17, v18, v19
	ds_write_b64 v24, v[16:17] offset:96
	ds_read_b128 v[16:19], v118 offset:17408
	ds_read_b128 v[20:23], v118 offset:17472
	s_waitcnt lgkmcnt(1)
; #define LAS __attribute__((address_space(3)))
; __device__ __forceinline__ unsigned pk_bf16(float lo, float hi) { unsigned r; asm volatile("v_cvt_pk_bf16_f32 %0, %1, %2" : "=v"(r) : "v"(lo), "v"(hi)); return r; }
; __device__ __forceinline__ f32x4 mfma16(bf16x8 a, bf16x8 b, f32x4 c) { return __builtin_amdgcn_mfma_f32_16x16x32_bf16(a, b, c, 0, 0, 0); }
; __device__ __forceinline__ void ret_out_unit(int b, int h, int c, LAS unsigned char* lds, const bf16_t* PROJ, const float* KV, bf16_t* H, int tid) {
;     ...
;     for (int cb = 0; cb < 8; ++cb) { f32x4 acc = {0.f, 0.f, 0.f, 0.f};
; #pragma unroll
;         for (int kk = 0; kk < 4; ++kk) { const bf16x8 kf = *(const LAS bf16x8*)(Ks + (16 * cb + fr) * 272 + (32 * kk + 8 * fq) * 2); acc = mfma16(kf, qf[kk], acc); }
;         float v[4];
; #pragma unroll
;         for (int t = 0; t < 4; ++t) { const int dl = i - (16 * cb + 4 * fq + t); v[t] = dl >= 0 ? acc[t] * 0.08838834764831845f * exp2f(lg2 * (float)dl) : 0.f; }
;         u32x2 w; w.x = pk_bf16(v[0], v[1]); w.y = pk_bf16(v[2], v[3]);
;         *(LAS u32x2*)(SC + i * 272 + (16 * cb + 4 * fq) * 2) = w; }
	v_mfma_f32_16x16x32_bf16 v[16:19], v[16:19], v[12:15], 0
	s_waitcnt lgkmcnt(0)
	v_mfma_f32_16x16x32_bf16 v[16:19], v[20:23], v[8:11], v[16:19]
	ds_read_b128 v[20:23], v118 offset:17536
	s_waitcnt lgkmcnt(0)
	v_mfma_f32_16x16x32_bf16 v[16:19], v[20:23], v[4:7], v[16:19]
	ds_read_b128 v[20:23], v118 offset:17600
	s_waitcnt lgkmcnt(0)
	v_mfma_f32_16x16x32_bf16 v[16:19], v[20:23], v[0:3], v[16:19]
	v_mul_f32_e32 v20, v113, v139
	v_cmp_gt_f32_e32 vcc, s34, v20
	s_nop 5
	v_mul_f32_e32 v16, 0x3db504f3, v16
	v_cndmask_b32_e32 v20, 0, v168, vcc
	v_fmac_f32_e32 v20, v113, v139
	v_exp_f32_e32 v20, v20
	v_cndmask_b32_e32 v21, 0, v171, vcc
	v_mul_f32_e32 v17, 0x3db504f3, v17
	v_mul_f32_e32 v18, 0x3db504f3, v18
	v_ldexp_f32 v20, v20, v21
	v_mul_f32_e32 v16, v20, v16
	v_mul_f32_e32 v20, v113, v140
	v_cmp_gt_f32_e32 vcc, s34, v20
	v_mul_f32_e32 v19, 0x3db504f3, v19
	v_cndmask_b32_e64 v16, 0, v16, s[70:71]
	v_cndmask_b32_e32 v20, 0, v168, vcc
	v_fmac_f32_e32 v20, v113, v140
	v_exp_f32_e32 v20, v20
	v_cndmask_b32_e32 v21, 0, v171, vcc
	v_ldexp_f32 v20, v20, v21
	v_mul_f32_e32 v17, v20, v17
	v_mul_f32_e32 v20, v113, v141
	v_cmp_gt_f32_e32 vcc, s34, v20
	v_cndmask_b32_e64 v17, 0, v17, s[72:73]
	v_cvt_pk_bf16_f32 v16, v16, v17
	s_nop 0
	v_cndmask_b32_e32 v20, 0, v168, vcc
	v_fmac_f32_e32 v20, v113, v141
	v_exp_f32_e32 v20, v20
	v_cndmask_b32_e32 v21, 0, v171, vcc
	v_ldexp_f32 v20, v20, v21
	v_mul_f32_e32 v18, v20, v18
	v_mul_f32_e32 v20, v113, v142
	v_cmp_gt_f32_e32 vcc, s34, v20
	v_cndmask_b32_e64 v18, 0, v18, s[74:75]
	s_nop 0
	v_cndmask_b32_e32 v20, 0, v168, vcc
	v_fmac_f32_e32 v20, v113, v142
	v_exp_f32_e32 v20, v20
	v_cndmask_b32_e32 v21, 0, v171, vcc
	v_ldexp_f32 v20, v20, v21
	v_mul_f32_e32 v19, v20, v19
	v_cndmask_b32_e64 v19, 0, v19, s[76:77]
	v_cvt_pk_bf16_f32 v17, v18, v19
	ds_write_b64 v24, v[16:17] offset:128
	ds_read_b128 v[16:19], v118 offset:21760
	ds_read_b128 v[20:23], v118 offset:21824
	s_waitcnt lgkmcnt(1)
	v_mfma_f32_16x16x32_bf16 v[16:19], v[16:19], v[12:15], 0
	s_waitcnt lgkmcnt(0)
	v_mfma_f32_16x16x32_bf16 v[16:19], v[20:23], v[8:11], v[16:19]
	ds_read_b128 v[20:23], v118 offset:21888
	s_waitcnt lgkmcnt(0)
	v_mfma_f32_16x16x32_bf16 v[16:19], v[20:23], v[4:7], v[16:19]
	ds_read_b128 v[20:23], v118 offset:21952
	s_waitcnt lgkmcnt(0)
	v_mfma_f32_16x16x32_bf16 v[16:19], v[20:23], v[0:3], v[16:19]
	v_mul_f32_e32 v20, v113, v143
	v_cmp_gt_f32_e32 vcc, s34, v20
	s_nop 5
	v_mul_f32_e32 v16, 0x3db504f3, v16
	v_cndmask_b32_e32 v20, 0, v168, vcc
	v_fmac_f32_e32 v20, v113, v143
	v_exp_f32_e32 v20, v20
	v_cndmask_b32_e32 v21, 0, v171, vcc
	v_mul_f32_e32 v17, 0x3db504f3, v17
	v_mul_f32_e32 v18, 0x3db504f3, v18
	v_ldexp_f32 v20, v20, v21
	v_mul_f32_e32 v16, v20, v16
	v_mul_f32_e32 v20, v113, v144
	v_cmp_gt_f32_e32 vcc, s34, v20
	v_mul_f32_e32 v19, 0x3db504f3, v19
	v_cndmask_b32_e64 v16, 0, v16, s[78:79]
	v_cndmask_b32_e32 v20, 0, v168, vcc
	v_fmac_f32_e32 v20, v113, v144
	v_exp_f32_e32 v20, v20
	v_cndmask_b32_e32 v21, 0, v171, vcc
	v_ldexp_f32 v20, v20, v21
	v_mul_f32_e32 v17, v20, v17
	v_mul_f32_e32 v20, v113, v145
	v_cmp_gt_f32_e32 vcc, s34, v20
	v_cndmask_b32_e64 v17, 0, v17, s[80:81]
	v_cvt_pk_bf16_f32 v16, v16, v17
	s_nop 0
	v_cndmask_b32_e32 v20, 0, v168, vcc
	v_fmac_f32_e32 v20, v113, v145
	v_exp_f32_e32 v20, v20
	v_cndmask_b32_e32 v21, 0, v171, vcc
	v_ldexp_f32 v20, v20, v21
	v_mul_f32_e32 v18, v20, v18
	v_mul_f32_e32 v20, v113, v146
	v_cmp_gt_f32_e32 vcc, s34, v20
	v_cndmask_b32_e64 v18, 0, v18, s[82:83]
	s_nop 0
	v_cndmask_b32_e32 v20, 0, v168, vcc
	v_fmac_f32_e32 v20, v113, v146
	v_exp_f32_e32 v20, v20
	v_cndmask_b32_e32 v21, 0, v171, vcc
	v_ldexp_f32 v20, v20, v21
	v_mul_f32_e32 v19, v20, v19
	v_cndmask_b32_e64 v19, 0, v19, s[84:85]
	v_cvt_pk_bf16_f32 v17, v18, v19
	ds_write_b64 v24, v[16:17] offset:160
	ds_read_b128 v[16:19], v118 offset:26112
	ds_read_b128 v[20:23], v118 offset:26176
	s_waitcnt lgkmcnt(1)
	v_mfma_f32_16x16x32_bf16 v[16:19], v[16:19], v[12:15], 0
	s_waitcnt lgkmcnt(0)
	v_mfma_f32_16x16x32_bf16 v[16:19], v[20:23], v[8:11], v[16:19]
	ds_read_b128 v[20:23], v118 offset:26240
	s_waitcnt lgkmcnt(0)
	v_mfma_f32_16x16x32_bf16 v[16:19], v[20:23], v[4:7], v[16:19]
	ds_read_b128 v[20:23], v118 offset:26304
	s_waitcnt lgkmcnt(0)
	v_mfma_f32_16x16x32_bf16 v[16:19], v[20:23], v[0:3], v[16:19]
	v_mul_f32_e32 v20, v113, v147
	v_cmp_gt_f32_e32 vcc, s34, v20
	s_nop 5
	v_mul_f32_e32 v16, 0x3db504f3, v16
	v_cndmask_b32_e32 v20, 0, v168, vcc
	v_fmac_f32_e32 v20, v113, v147
	v_exp_f32_e32 v20, v20
	v_cndmask_b32_e32 v21, 0, v171, vcc
	v_mul_f32_e32 v17, 0x3db504f3, v17
	v_mul_f32_e32 v18, 0x3db504f3, v18
	v_ldexp_f32 v20, v20, v21
	v_mul_f32_e32 v16, v20, v16
	v_mul_f32_e32 v20, v113, v148
	v_cmp_gt_f32_e32 vcc, s34, v20
	v_mul_f32_e32 v19, 0x3db504f3, v19
	v_cndmask_b32_e64 v16, 0, v16, s[86:87]
	v_cndmask_b32_e32 v20, 0, v168, vcc
	v_fmac_f32_e32 v20, v113, v148
	v_exp_f32_e32 v20, v20
	v_cndmask_b32_e32 v21, 0, v171, vcc
	v_ldexp_f32 v20, v20, v21
	v_mul_f32_e32 v17, v20, v17
	v_mul_f32_e32 v20, v113, v149
	v_cmp_gt_f32_e32 vcc, s34, v20
	v_cndmask_b32_e64 v17, 0, v17, s[88:89]
	v_cvt_pk_bf16_f32 v16, v16, v17
	s_nop 0
	v_cndmask_b32_e32 v20, 0, v168, vcc
	v_fmac_f32_e32 v20, v113, v149
	v_exp_f32_e32 v20, v20
	v_cndmask_b32_e32 v21, 0, v171, vcc
	v_ldexp_f32 v20, v20, v21
	v_mul_f32_e32 v18, v20, v18
	v_mul_f32_e32 v20, v113, v150
	v_cmp_gt_f32_e32 vcc, s34, v20
	v_cndmask_b32_e64 v18, 0, v18, s[90:91]
	s_nop 0
	v_cndmask_b32_e32 v20, 0, v168, vcc
	v_fmac_f32_e32 v20, v113, v150
	v_exp_f32_e32 v20, v20
	v_cndmask_b32_e32 v21, 0, v171, vcc
	v_ldexp_f32 v20, v20, v21
	v_mul_f32_e32 v19, v20, v19
	v_cndmask_b32_e64 v19, 0, v19, s[92:93]
	v_cvt_pk_bf16_f32 v17, v18, v19
	ds_write_b64 v24, v[16:17] offset:192
	ds_read_b128 v[16:19], v118 offset:30464
	ds_read_b128 v[20:23], v118 offset:30528
	s_waitcnt lgkmcnt(1)
; #define LAS __attribute__((address_space(3)))
; __device__ __forceinline__ unsigned pk_bf16(float lo, float hi) { unsigned r; asm volatile("v_cvt_pk_bf16_f32 %0, %1, %2" : "=v"(r) : "v"(lo), "v"(hi)); return r; }
; __device__ __forceinline__ f32x4 mfma16(bf16x8 a, bf16x8 b, f32x4 c) { return __builtin_amdgcn_mfma_f32_16x16x32_bf16(a, b, c, 0, 0, 0); }
; __device__ __forceinline__ void lds_wave_sync() { asm volatile("s_waitcnt lgkmcnt(0)" ::: "memory"); }
; __device__ __forceinline__ void ret_out_unit(int b, int h, int c, LAS unsigned char* lds, const bf16_t* PROJ, const float* KV, bf16_t* H, int tid) {
;     ...
;     for (int cb = 0; cb < 8; ++cb) { f32x4 acc = {0.f, 0.f, 0.f, 0.f};
; #pragma unroll
;         for (int kk = 0; kk < 4; ++kk) { const bf16x8 kf = *(const LAS bf16x8*)(Ks + (16 * cb + fr) * 272 + (32 * kk + 8 * fq) * 2); acc = mfma16(kf, qf[kk], acc); }
;         float v[4];
; #pragma unroll
;         for (int t = 0; t < 4; ++t) { const int dl = i - (16 * cb + 4 * fq + t); v[t] = dl >= 0 ? acc[t] * 0.08838834764831845f * exp2f(lg2 * (float)dl) : 0.f; }
;         u32x2 w; w.x = pk_bf16(v[0], v[1]); w.y = pk_bf16(v[2], v[3]);
;         *(LAS u32x2*)(SC + i * 272 + (16 * cb + 4 * fq) * 2) = w; }
;     lds_wave_sync();
;     f32x4 o1[8], o2[8];
; #pragma unroll
;     for (int cb = 0; cb < 8; ++cb) { o1[cb] = (f32x4){0.f, 0.f, 0.f, 0.f}; o2[cb] = (f32x4){0.f, 0.f, 0.f, 0.f}; }
; #pragma unroll
;     for (int kk = 0; kk < 4; ++kk) { const bf16x8 sf = *(const LAS bf16x8*)(SC + i * 272 + (32 * kk + 8 * fq) * 2);
; #pragma unroll
;         for (int cb = 0; cb < 8; ++cb) { const bf16x8 vf = *(const LAS bf16x8*)(VT + (16 * cb + fr) * 272 + (32 * kk + 8 * fq) * 2); o1[cb] = mfma16(vf, sf, o1[cb]);
;             const bf16x8 tf = *(const LAS bf16x8*)(ST + (16 * cb + fr) * 272 + (32 * kk + 8 * fq) * 2); o2[cb] = mfma16(tf, qf[kk], o2[cb]); } }
	v_mfma_f32_16x16x32_bf16 v[16:19], v[16:19], v[12:15], 0
	s_waitcnt lgkmcnt(0)
	v_mfma_f32_16x16x32_bf16 v[16:19], v[20:23], v[8:11], v[16:19]
	ds_read_b128 v[20:23], v118 offset:30592
	s_waitcnt lgkmcnt(0)
	v_mfma_f32_16x16x32_bf16 v[16:19], v[20:23], v[4:7], v[16:19]
	ds_read_b128 v[20:23], v118 offset:30656
	s_waitcnt lgkmcnt(0)
	v_mfma_f32_16x16x32_bf16 v[16:19], v[20:23], v[0:3], v[16:19]
	v_mul_f32_e32 v20, v113, v151
	v_cmp_gt_f32_e32 vcc, s34, v20
	s_nop 5
	v_mul_f32_e32 v16, 0x3db504f3, v16
	v_cndmask_b32_e32 v20, 0, v168, vcc
	v_fmac_f32_e32 v20, v113, v151
	v_exp_f32_e32 v20, v20
	v_cndmask_b32_e32 v21, 0, v171, vcc
	v_mul_f32_e32 v17, 0x3db504f3, v17
	v_mul_f32_e32 v18, 0x3db504f3, v18
	v_ldexp_f32 v20, v20, v21
	v_mul_f32_e32 v16, v20, v16
	v_mul_f32_e32 v20, v113, v152
	v_cmp_gt_f32_e32 vcc, s34, v20
	v_mul_f32_e32 v19, 0x3db504f3, v19
	v_cndmask_b32_e64 v16, 0, v16, s[94:95]
	v_cndmask_b32_e32 v20, 0, v168, vcc
	v_fmac_f32_e32 v20, v113, v152
	v_exp_f32_e32 v20, v20
	v_cndmask_b32_e32 v21, 0, v171, vcc
	v_ldexp_f32 v20, v20, v21
	v_mul_f32_e32 v17, v20, v17
	v_mul_f32_e32 v20, v113, v153
	v_cmp_gt_f32_e32 vcc, s34, v20
	v_cndmask_b32_e64 v17, 0, v17, s[96:97]
	v_cvt_pk_bf16_f32 v16, v16, v17
	s_nop 0
	v_cndmask_b32_e32 v20, 0, v168, vcc
	v_fmac_f32_e32 v20, v113, v153
	v_exp_f32_e32 v20, v20
	v_cndmask_b32_e32 v21, 0, v171, vcc
	v_ldexp_f32 v20, v20, v21
	v_mul_f32_e32 v18, v20, v18
	v_mul_f32_e32 v20, v113, v154
	v_cmp_gt_f32_e32 vcc, s34, v20
	v_cndmask_b32_e64 v18, 0, v18, s[0:1]
	s_nop 0
	v_cndmask_b32_e32 v20, 0, v168, vcc
	v_fmac_f32_e32 v20, v113, v154
	v_exp_f32_e32 v20, v20
	v_cndmask_b32_e32 v21, 0, v171, vcc
	v_ldexp_f32 v20, v20, v21
	v_mul_f32_e32 v19, v20, v19
	v_cndmask_b32_e64 v19, 0, v19, s[4:5]
	v_cvt_pk_bf16_f32 v17, v18, v19
	ds_write_b64 v24, v[16:17] offset:224
	s_waitcnt lgkmcnt(0)
	ds_read_b128 v[16:19], v128
	ds_read_b128 v[20:23], v118 offset:34816
	s_waitcnt lgkmcnt(0)
	v_mfma_f32_16x16x32_bf16 v[32:35], v[20:23], v[16:19], 0
	ds_read_b128 v[20:23], v202
	s_waitcnt lgkmcnt(0)
	v_mfma_f32_16x16x32_bf16 v[212:215], v[20:23], v[12:15], 0
	ds_read_b128 v[20:23], v118 offset:39168
	s_waitcnt lgkmcnt(0)
	v_mfma_f32_16x16x32_bf16 v[72:75], v[20:23], v[16:19], 0
	ds_read_b128 v[20:23], v202 offset:4352
	s_waitcnt lgkmcnt(0)
	v_mfma_f32_16x16x32_bf16 v[76:79], v[20:23], v[12:15], 0
	ds_read_b128 v[20:23], v118 offset:43520
	s_waitcnt lgkmcnt(0)
	v_mfma_f32_16x16x32_bf16 v[64:67], v[20:23], v[16:19], 0
	ds_read_b128 v[20:23], v202 offset:8704
	s_waitcnt lgkmcnt(0)
	v_mfma_f32_16x16x32_bf16 v[68:71], v[20:23], v[12:15], 0
	ds_read_b128 v[20:23], v118 offset:47872
	s_waitcnt lgkmcnt(0)
	v_mfma_f32_16x16x32_bf16 v[52:55], v[20:23], v[16:19], 0
	ds_read_b128 v[20:23], v202 offset:13056
	s_waitcnt lgkmcnt(0)
	v_mfma_f32_16x16x32_bf16 v[56:59], v[20:23], v[12:15], 0
	ds_read_b128 v[20:23], v118 offset:52224
	s_waitcnt lgkmcnt(0)
	v_mfma_f32_16x16x32_bf16 v[44:47], v[20:23], v[16:19], 0
	ds_read_b128 v[20:23], v202 offset:17408
	s_waitcnt lgkmcnt(0)
	v_mfma_f32_16x16x32_bf16 v[48:51], v[20:23], v[12:15], 0
	ds_read_b128 v[20:23], v118 offset:56576
	s_waitcnt lgkmcnt(0)
	v_mfma_f32_16x16x32_bf16 v[36:39], v[20:23], v[16:19], 0
	ds_read_b128 v[20:23], v202 offset:21760
	s_waitcnt lgkmcnt(0)
	v_mfma_f32_16x16x32_bf16 v[40:43], v[20:23], v[12:15], 0
	ds_read_b128 v[20:23], v118 offset:60928
	s_waitcnt lgkmcnt(0)
	v_mfma_f32_16x16x32_bf16 v[24:27], v[20:23], v[16:19], 0
	ds_read_b128 v[20:23], v202 offset:26112
	s_waitcnt lgkmcnt(0)
	v_mfma_f32_16x16x32_bf16 v[28:31], v[20:23], v[12:15], 0
	ds_read_b128 v[20:23], v118 offset:65280
	s_waitcnt lgkmcnt(0)
	v_mfma_f32_16x16x32_bf16 v[20:23], v[20:23], v[16:19], 0
	ds_read_b128 v[16:19], v202 offset:30464
	s_waitcnt lgkmcnt(0)
	v_mfma_f32_16x16x32_bf16 v[16:19], v[16:19], v[12:15], 0
	ds_read_b128 v[60:63], v128 offset:64
	ds_read_b128 v[12:15], v118 offset:34880
	s_waitcnt lgkmcnt(0)
	v_mfma_f32_16x16x32_bf16 v[32:35], v[12:15], v[60:63], v[32:35]
	v_add_u32_e32 v12, v156, v155
	ds_read_b128 v[12:15], v12
	s_waitcnt lgkmcnt(0)
	v_mfma_f32_16x16x32_bf16 v[12:15], v[12:15], v[8:11], v[212:215]
	s_nop 2
	ds_read_b128 v[212:215], v118 offset:39232
	s_waitcnt lgkmcnt(0)
	v_mfma_f32_16x16x32_bf16 v[72:75], v[212:215], v[60:63], v[72:75]
	ds_read_b128 v[212:215], v203 offset:4352
	s_waitcnt lgkmcnt(0)
	v_mfma_f32_16x16x32_bf16 v[76:79], v[212:215], v[8:11], v[76:79]
	ds_read_b128 v[212:215], v118 offset:43584
	s_waitcnt lgkmcnt(0)
	v_mfma_f32_16x16x32_bf16 v[64:67], v[212:215], v[60:63], v[64:67]
	ds_read_b128 v[212:215], v203 offset:8704
	s_waitcnt lgkmcnt(0)
	v_mfma_f32_16x16x32_bf16 v[68:71], v[212:215], v[8:11], v[68:71]
	ds_read_b128 v[212:215], v118 offset:47936
	s_waitcnt lgkmcnt(0)
	v_mfma_f32_16x16x32_bf16 v[52:55], v[212:215], v[60:63], v[52:55]
	ds_read_b128 v[212:215], v203 offset:13056
	s_waitcnt lgkmcnt(0)
	v_mfma_f32_16x16x32_bf16 v[56:59], v[212:215], v[8:11], v[56:59]
	ds_read_b128 v[212:215], v118 offset:52288
	s_waitcnt lgkmcnt(0)
	v_mfma_f32_16x16x32_bf16 v[44:47], v[212:215], v[60:63], v[44:47]
	ds_read_b128 v[212:215], v203 offset:17408
	s_waitcnt lgkmcnt(0)
	v_mfma_f32_16x16x32_bf16 v[48:51], v[212:215], v[8:11], v[48:51]
	ds_read_b128 v[212:215], v118 offset:56640
	s_waitcnt lgkmcnt(0)
	v_mfma_f32_16x16x32_bf16 v[36:39], v[212:215], v[60:63], v[36:39]
	ds_read_b128 v[212:215], v203 offset:21760
	s_waitcnt lgkmcnt(0)
	v_mfma_f32_16x16x32_bf16 v[40:43], v[212:215], v[8:11], v[40:43]
	ds_read_b128 v[212:215], v118 offset:60992
	s_waitcnt lgkmcnt(0)
	v_mfma_f32_16x16x32_bf16 v[24:27], v[212:215], v[60:63], v[24:27]
	ds_read_b128 v[212:215], v203 offset:26112
	s_waitcnt lgkmcnt(0)
; #define LAS __attribute__((address_space(3)))
; __device__ __forceinline__ f32x4 mfma16(bf16x8 a, bf16x8 b, f32x4 c) { return __builtin_amdgcn_mfma_f32_16x16x32_bf16(a, b, c, 0, 0, 0); }
; __device__ __forceinline__ void ret_out_unit(int b, int h, int c, LAS unsigned char* lds, const bf16_t* PROJ, const float* KV, bf16_t* H, int tid) {
;     ...
; #pragma unroll
;     for (int kk = 0; kk < 4; ++kk) { const bf16x8 sf = *(const LAS bf16x8*)(SC + i * 272 + (32 * kk + 8 * fq) * 2);
; #pragma unroll
;         for (int cb = 0; cb < 8; ++cb) { const bf16x8 vf = *(const LAS bf16x8*)(VT + (16 * cb + fr) * 272 + (32 * kk + 8 * fq) * 2); o1[cb] = mfma16(vf, sf, o1[cb]);
;             const bf16x8 tf = *(const LAS bf16x8*)(ST + (16 * cb + fr) * 272 + (32 * kk + 8 * fq) * 2); o2[cb] = mfma16(tf, qf[kk], o2[cb]); } }
	v_mfma_f32_16x16x32_bf16 v[28:31], v[212:215], v[8:11], v[28:31]
	ds_read_b128 v[212:215], v118 offset:65344
	s_waitcnt lgkmcnt(0)
	v_mfma_f32_16x16x32_bf16 v[20:23], v[212:215], v[60:63], v[20:23]
	ds_read_b128 v[60:63], v203 offset:30464
	s_waitcnt lgkmcnt(0)
	v_mfma_f32_16x16x32_bf16 v[60:63], v[60:63], v[8:11], v[16:19]
	ds_read_b128 v[8:11], v128 offset:128
	s_nop 1
	ds_read_b128 v[16:19], v118 offset:34944
	s_waitcnt lgkmcnt(0)
	v_mfma_f32_16x16x32_bf16 v[32:35], v[16:19], v[8:11], v[32:35]
	v_add_u32_e32 v16, v156, v157
	ds_read_b128 v[16:19], v16
	s_waitcnt lgkmcnt(0)
	v_mfma_f32_16x16x32_bf16 v[212:215], v[16:19], v[4:7], v[12:15]
	s_nop 2
	ds_read_b128 v[12:15], v118 offset:39296
	ds_read_b128 v[16:19], v204 offset:26112
	s_waitcnt lgkmcnt(1)
	v_mfma_f32_16x16x32_bf16 v[72:75], v[12:15], v[8:11], v[72:75]
	ds_read_b128 v[12:15], v204 offset:4352
	s_waitcnt lgkmcnt(0)
	v_mfma_f32_16x16x32_bf16 v[76:79], v[12:15], v[4:7], v[76:79]
	ds_read_b128 v[12:15], v118 offset:43648
	s_waitcnt lgkmcnt(0)
	v_mfma_f32_16x16x32_bf16 v[64:67], v[12:15], v[8:11], v[64:67]
	ds_read_b128 v[12:15], v204 offset:8704
	s_waitcnt lgkmcnt(0)
	v_mfma_f32_16x16x32_bf16 v[68:71], v[12:15], v[4:7], v[68:71]
	ds_read_b128 v[12:15], v118 offset:48000
	s_waitcnt lgkmcnt(0)
	v_mfma_f32_16x16x32_bf16 v[52:55], v[12:15], v[8:11], v[52:55]
	ds_read_b128 v[12:15], v204 offset:13056
	s_waitcnt lgkmcnt(0)
	v_mfma_f32_16x16x32_bf16 v[56:59], v[12:15], v[4:7], v[56:59]
	ds_read_b128 v[12:15], v118 offset:52352
	s_waitcnt lgkmcnt(0)
	v_mfma_f32_16x16x32_bf16 v[44:47], v[12:15], v[8:11], v[44:47]
	ds_read_b128 v[12:15], v204 offset:17408
	s_waitcnt lgkmcnt(0)
	v_mfma_f32_16x16x32_bf16 v[48:51], v[12:15], v[4:7], v[48:51]
	ds_read_b128 v[12:15], v118 offset:56704
	s_waitcnt lgkmcnt(0)
	v_mfma_f32_16x16x32_bf16 v[36:39], v[12:15], v[8:11], v[36:39]
	ds_read_b128 v[12:15], v204 offset:21760
	s_waitcnt lgkmcnt(0)
	v_mfma_f32_16x16x32_bf16 v[40:43], v[12:15], v[4:7], v[40:43]
	ds_read_b128 v[12:15], v118 offset:61056
	s_waitcnt lgkmcnt(0)
	v_mfma_f32_16x16x32_bf16 v[12:15], v[12:15], v[8:11], v[24:27]
	s_nop 2
	ds_read_b128 v[24:27], v118 offset:65408
	s_waitcnt lgkmcnt(0)
	v_mfma_f32_16x16x32_bf16 v[8:11], v[24:27], v[8:11], v[20:23]
	s_nop 2
	ds_read_b128 v[20:23], v204 offset:30464
	v_mfma_f32_16x16x32_bf16 v[16:19], v[16:19], v[4:7], v[28:31]
	s_waitcnt lgkmcnt(0)
	v_mfma_f32_16x16x32_bf16 v[4:7], v[20:23], v[4:7], v[60:63]
	ds_read_b128 v[20:23], v128 offset:192
	ds_read_b128 v[24:27], v118 offset:35008
	v_add_u32_e32 v28, v156, v158
	ds_read_b128 v[28:31], v28
	s_waitcnt lgkmcnt(1)
	v_mfma_f32_16x16x32_bf16 v[24:27], v[24:27], v[20:23], v[32:35]
	s_nop 2
	ds_read_b128 v[32:35], v118 offset:39360
	s_waitcnt lgkmcnt(0)
	v_mfma_f32_16x16x32_bf16 v[60:63], v[32:35], v[20:23], v[72:75]
	ds_read_b128 v[32:35], v205 offset:4352
	s_waitcnt lgkmcnt(0)
	v_mfma_f32_16x16x32_bf16 v[72:75], v[32:35], v[0:3], v[76:79]
	ds_read_b128 v[32:35], v118 offset:43712
	s_waitcnt lgkmcnt(0)
	v_mfma_f32_16x16x32_bf16 v[64:67], v[32:35], v[20:23], v[64:67]
	ds_read_b128 v[32:35], v205 offset:8704
	s_waitcnt lgkmcnt(0)
	v_mfma_f32_16x16x32_bf16 v[68:71], v[32:35], v[0:3], v[68:71]
	ds_read_b128 v[32:35], v118 offset:48064
	s_waitcnt lgkmcnt(0)
	v_mfma_f32_16x16x32_bf16 v[52:55], v[32:35], v[20:23], v[52:55]
	ds_read_b128 v[32:35], v205 offset:13056
	s_waitcnt lgkmcnt(0)
	v_mfma_f32_16x16x32_bf16 v[56:59], v[32:35], v[0:3], v[56:59]
	ds_read_b128 v[32:35], v118 offset:52416
	s_waitcnt lgkmcnt(0)
	v_mfma_f32_16x16x32_bf16 v[44:47], v[32:35], v[20:23], v[44:47]
	ds_read_b128 v[32:35], v205 offset:17408
	s_waitcnt lgkmcnt(0)
	v_mfma_f32_16x16x32_bf16 v[48:51], v[32:35], v[0:3], v[48:51]
	ds_read_b128 v[32:35], v118 offset:56768
	s_waitcnt lgkmcnt(0)
	v_mfma_f32_16x16x32_bf16 v[36:39], v[32:35], v[20:23], v[36:39]
	ds_read_b128 v[32:35], v205 offset:21760
	s_waitcnt lgkmcnt(0)
	v_mfma_f32_16x16x32_bf16 v[40:43], v[32:35], v[0:3], v[40:43]
	ds_read_b128 v[32:35], v118 offset:61120
	s_waitcnt lgkmcnt(0)
	v_mfma_f32_16x16x32_bf16 v[76:79], v[32:35], v[20:23], v[12:15]
	s_nop 2
	ds_read_b128 v[12:15], v205 offset:26112
	v_mfma_f32_16x16x32_bf16 v[28:31], v[28:31], v[0:3], v[212:215]
	s_waitcnt lgkmcnt(0)
	v_mfma_f32_16x16x32_bf16 v[212:215], v[12:15], v[0:3], v[16:19]
	ds_read_b128 v[12:15], v118 offset:65472
	s_waitcnt lgkmcnt(0)
	v_mfma_f32_16x16x32_bf16 v[216:219], v[12:15], v[20:23], v[8:11]
	s_nop 2
	ds_read_b128 v[8:11], v205 offset:30464
	s_waitcnt lgkmcnt(0)
; __device__ __forceinline__ unsigned pk_bf16(float lo, float hi) { unsigned r; asm volatile("v_cvt_pk_bf16_f32 %0, %1, %2" : "=v"(r) : "v"(lo), "v"(hi)); return r; }
; __device__ __forceinline__ float bflo(unsigned w) { return __uint_as_float(w << 16); }
; __device__ __forceinline__ float bfhi(unsigned w) { return __uint_as_float(w & 0xffff0000u); }
; __device__ __forceinline__ float silu_f(float x) { return x / (1.0f + __expf(-x)); }
; __device__ __forceinline__ void ret_out_unit(int b, int h, int c, LAS unsigned char* lds, const bf16_t* PROJ, const float* KV, bf16_t* H, int tid) {
;     ...
;     const float rd = exp2f(lg2 * (float)(i + 1));
;     float ss = 0.f;
; #pragma unroll
;     for (int cb = 0; cb < 8; ++cb) { o1[cb] = o1[cb] + o2[cb] * rd; ss += o1[cb][0] * o1[cb][0] + o1[cb][1] * o1[cb][1] + o1[cb][2] * o1[cb][2] + o1[cb][3] * o1[cb][3]; }
;     ss += __shfl_xor(ss, 16); ss += __shfl_xor(ss, 32);
;     const float rinv = rsqrtf(ss * (1.0f / 128.0f) + EPS);
; #pragma unroll
;     for (int cb = 0; cb < 8; ++cb) { const u32x2 gw = *(const u32x2*)(PROJ + qrow * EIN + 3072 + h * 128 + 16 * cb + 4 * fq);
;         const float g0 = silu_f(bflo(gw.x)), g1 = silu_f(bfhi(gw.x)), g2 = silu_f(bflo(gw.y)), g3 = silu_f(bfhi(gw.y));
;         u32x2 w; w.x = pk_bf16(o1[cb][0] * rinv * g0, o1[cb][1] * rinv * g1); w.y = pk_bf16(o1[cb][2] * rinv * g2, o1[cb][3] * rinv * g3);
;         *(u32x2*)(H + qrow * DM + h * 128 + 16 * cb + 4 * fq) = w; }
	v_mfma_f32_16x16x32_bf16 v[2:5], v[8:11], v[0:3], v[4:7]
	v_mul_f32_e32 v0, v113, v159
	v_cmp_gt_f32_e32 vcc, s34, v0
	s_nop 1
	v_cndmask_b32_e32 v0, 0, v168, vcc
	v_fmac_f32_e32 v0, v113, v159
	v_exp_f32_e32 v0, v0
	v_cndmask_b32_e32 v1, 0, v171, vcc
	v_mov_b32_e32 v113, v129
	v_ldexp_f32 v6, v0, v1
	v_pk_fma_f32 v[32:33], v[6:7], v[30:31], v[26:27] op_sel_hi:[0,1,1]
	v_pk_fma_f32 v[34:35], v[6:7], v[28:29], v[24:25] op_sel_hi:[0,1,1]
	v_pk_fma_f32 v[30:31], v[6:7], v[72:73], v[60:61] op_sel_hi:[0,1,1]
	v_mov_b32_e32 v8, v35
	v_mov_b32_e32 v9, v31
	v_pk_fma_f32 v[28:29], v[6:7], v[74:75], v[62:63] op_sel_hi:[0,1,1]
	v_mov_b32_e32 v0, v34
	v_mov_b32_e32 v1, v30
	v_pk_mul_f32 v[8:9], v[8:9], v[8:9]
	v_pk_fma_f32 v[26:27], v[6:7], v[68:69], v[64:65] op_sel_hi:[0,1,1]
	v_pk_fma_f32 v[0:1], v[0:1], v[0:1], v[8:9]
	v_mov_b32_e32 v8, v32
	v_mov_b32_e32 v9, v28
	v_pk_fma_f32 v[0:1], v[8:9], v[8:9], v[0:1]
	v_mov_b32_e32 v8, v33
	v_mov_b32_e32 v9, v29
	v_pk_fma_f32 v[22:23], v[6:7], v[56:57], v[52:53] op_sel_hi:[0,1,1]
	v_pk_fma_f32 v[60:61], v[8:9], v[8:9], v[0:1]
	v_mov_b32_e32 v8, v27
	v_mov_b32_e32 v9, v23
	v_pk_fma_f32 v[24:25], v[6:7], v[70:71], v[66:67] op_sel_hi:[0,1,1]
	v_pk_fma_f32 v[20:21], v[6:7], v[58:59], v[54:55] op_sel_hi:[0,1,1]
	v_mov_b32_e32 v0, v26
	v_mov_b32_e32 v1, v22
	v_pk_mul_f32 v[8:9], v[8:9], v[8:9]
	v_pk_fma_f32 v[18:19], v[6:7], v[48:49], v[44:45] op_sel_hi:[0,1,1]
	v_pk_fma_f32 v[0:1], v[0:1], v[0:1], v[8:9]
	v_mov_b32_e32 v8, v24
	v_mov_b32_e32 v9, v20
	v_pk_fma_f32 v[0:1], v[8:9], v[8:9], v[0:1]
	v_mov_b32_e32 v8, v25
	v_mov_b32_e32 v9, v21
	v_pk_fma_f32 v[14:15], v[6:7], v[40:41], v[36:37] op_sel_hi:[0,1,1]
	v_pk_fma_f32 v[52:53], v[8:9], v[8:9], v[0:1]
	v_mov_b32_e32 v8, v19
	v_mov_b32_e32 v9, v15
	v_pk_fma_f32 v[16:17], v[6:7], v[50:51], v[46:47] op_sel_hi:[0,1,1]
	v_pk_fma_f32 v[12:13], v[6:7], v[42:43], v[38:39] op_sel_hi:[0,1,1]
	v_mov_b32_e32 v0, v18
	v_mov_b32_e32 v1, v14
	v_pk_mul_f32 v[8:9], v[8:9], v[8:9]
	v_pk_fma_f32 v[10:11], v[6:7], v[212:213], v[76:77] op_sel_hi:[0,1,1]
	v_pk_fma_f32 v[0:1], v[0:1], v[0:1], v[8:9]
	v_mov_b32_e32 v8, v16
	v_mov_b32_e32 v9, v12
	v_pk_fma_f32 v[0:1], v[8:9], v[8:9], v[0:1]
	v_mov_b32_e32 v8, v17
	v_mov_b32_e32 v9, v13
	v_pk_fma_f32 v[2:3], v[6:7], v[2:3], v[216:217] op_sel_hi:[0,1,1]
	v_pk_fma_f32 v[36:37], v[8:9], v[8:9], v[0:1]
	v_pk_fma_f32 v[8:9], v[6:7], v[214:215], v[78:79] op_sel_hi:[0,1,1]
	v_pk_fma_f32 v[0:1], v[6:7], v[4:5], v[218:219] op_sel_hi:[0,1,1]
	v_mov_b32_e32 v6, v11
	v_mov_b32_e32 v7, v3
	v_mov_b32_e32 v4, v10
	v_mov_b32_e32 v5, v2
	v_pk_mul_f32 v[6:7], v[6:7], v[6:7]
	s_nop 0
	v_pk_fma_f32 v[4:5], v[4:5], v[4:5], v[6:7]
	v_mov_b32_e32 v6, v8
	v_mov_b32_e32 v7, v0
	v_pk_fma_f32 v[4:5], v[6:7], v[6:7], v[4:5]
	v_mov_b32_e32 v6, v9
	v_mov_b32_e32 v7, v1
	v_pk_fma_f32 v[4:5], v[6:7], v[6:7], v[4:5]
	v_add_f32_e32 v6, v60, v61
	v_add_f32_e32 v6, v6, v52
	v_add_f32_e32 v6, v6, v53
	v_add_f32_e32 v6, v6, v36
	v_add_f32_e32 v6, v6, v37
	v_add_f32_e32 v4, v6, v4
	v_and_b32_e32 v6, 64, v166
	v_add_f32_e32 v4, v4, v5
	v_xor_b32_e32 v5, 16, v166
	v_add_u32_e32 v6, 64, v6
	v_cmp_lt_i32_e32 vcc, v5, v6
	v_lshl_add_u64 v[36:37], v[116:117], 0, v[112:113]
	s_nop 0
	v_cndmask_b32_e32 v5, v166, v5, vcc
	v_lshlrev_b32_e32 v5, 2, v5
	ds_bpermute_b32 v5, v5, v4
	s_waitcnt lgkmcnt(0)
	v_add_f32_e32 v4, v4, v5
	v_xor_b32_e32 v5, 32, v166
	v_cmp_lt_i32_e32 vcc, v5, v6
	v_lshlrev_b64 v[6:7], 12, v[114:115]
	v_lshl_add_u64 v[6:7], s[18:19], 0, v[6:7]
	v_cndmask_b32_e32 v5, v166, v5, vcc
	v_lshlrev_b32_e32 v5, 2, v5
	ds_bpermute_b32 v5, v5, v4
	v_lshl_add_u64 v[6:7], v[6:7], 0, v[112:113]
	s_waitcnt lgkmcnt(0)
	v_add_f32_e32 v4, v4, v5
	v_fmamk_f32 v4, v4, 0x3c000000, v163
	v_cmp_gt_f32_e32 vcc, s23, v4
	v_mul_f32_e32 v5, 0x4b800000, v4
	s_nop 0
	v_cndmask_b32_e32 v4, v4, v5, vcc
	v_rsq_f32_e32 v4, v4
	s_nop 0
	v_mul_f32_e32 v5, 0x45800000, v4
	v_cndmask_b32_e32 v38, v4, v5, vcc
	v_lshl_add_u64 v[4:5], v[36:37], 0, s[14:15]
	v_add_co_u32_e32 v36, vcc, s33, v36
	v_mul_f32_e32 v34, v34, v38
	s_nop 0
	v_addc_co_u32_e32 v37, vcc, 0, v37, vcc
	global_load_dwordx2 v[40:41], v[36:37], off offset:2048
	v_mul_f32_e32 v35, v35, v38
	v_mul_f32_e32 v32, v32, v38
	v_mul_f32_e32 v33, v33, v38
	v_mul_f32_e32 v30, v30, v38
	v_mul_f32_e32 v31, v31, v38
	v_mul_f32_e32 v28, v28, v38
	v_mul_f32_e32 v29, v29, v38
	v_mul_f32_e32 v26, v26, v38
	v_mul_f32_e32 v27, v27, v38
	v_mul_f32_e32 v24, v24, v38
	v_mul_f32_e32 v25, v25, v38
	v_mul_f32_e32 v22, v22, v38
	v_mul_f32_e32 v23, v23, v38
	v_mul_f32_e32 v20, v20, v38
	v_mul_f32_e32 v21, v21, v38
	v_mul_f32_e32 v18, v18, v38
	v_mul_f32_e32 v19, v19, v38
	v_mul_f32_e32 v16, v16, v38
	v_mul_f32_e32 v17, v17, v38
	v_mul_f32_e32 v14, v14, v38
	v_mul_f32_e32 v15, v15, v38
	v_mul_f32_e32 v12, v12, v38
	v_mul_f32_e32 v13, v13, v38
	v_mul_f32_e32 v10, v10, v38
	v_mul_f32_e32 v11, v11, v38
	v_mul_f32_e32 v8, v8, v38
	v_mul_f32_e32 v9, v9, v38
	v_mul_f32_e32 v2, v2, v38
	v_mul_f32_e32 v3, v3, v38
	v_mul_f32_e32 v0, v0, v38
	v_mul_f32_e32 v1, v1, v38
	s_waitcnt vmcnt(0)
	v_lshlrev_b32_e32 v36, 16, v40
	v_mul_f32_e32 v37, 0xbfb8aa3b, v36
	v_exp_f32_e32 v37, v37
	s_nop 0
	v_add_f32_e32 v37, 1.0, v37
	v_rcp_f32_e32 v42, v37
	s_nop 0
	v_mul_f32_e32 v36, v36, v42
	v_and_b32_e32 v37, 0xffff0000, v40
	v_mul_f32_e32 v39, 0xbfb8aa3b, v37
	v_exp_f32_e32 v39, v39
	v_mul_f32_e32 v34, v36, v34
	v_add_f32_e32 v39, 1.0, v39
	v_rcp_f32_e32 v42, v39
	s_nop 0
	v_mul_f32_e32 v37, v37, v42
	v_lshlrev_b32_e32 v39, 16, v41
	v_mul_f32_e32 v40, 0xbfb8aa3b, v39
	v_exp_f32_e32 v40, v40
	v_mul_f32_e32 v35, v37, v35
	v_cvt_pk_bf16_f32 v34, v34, v35
	v_add_f32_e32 v40, 1.0, v40
	v_rcp_f32_e32 v43, v40
	s_nop 0
	v_mul_f32_e32 v39, v39, v43
	v_and_b32_e32 v40, 0xffff0000, v41
	v_mul_f32_e32 v41, 0xbfb8aa3b, v40
	v_exp_f32_e32 v41, v41
	v_mul_f32_e32 v32, v39, v32
	v_add_f32_e32 v41, 1.0, v41
	v_rcp_f32_e32 v43, v41
	s_nop 0
	v_mul_f32_e32 v40, v40, v43
	v_mul_f32_e32 v33, v40, v33
	v_cvt_pk_bf16_f32 v35, v32, v33
	global_load_dwordx2 v[32:33], v[4:5], off offset:32
	s_nop 0
	global_store_dwordx2 v[6:7], v[34:35], off
	s_waitcnt vmcnt(1)
; __device__ __forceinline__ unsigned pk_bf16(float lo, float hi) { unsigned r; asm volatile("v_cvt_pk_bf16_f32 %0, %1, %2" : "=v"(r) : "v"(lo), "v"(hi)); return r; }
; __device__ __forceinline__ float bflo(unsigned w) { return __uint_as_float(w << 16); }
; __device__ __forceinline__ float bfhi(unsigned w) { return __uint_as_float(w & 0xffff0000u); }
; __device__ __forceinline__ float silu_f(float x) { return x / (1.0f + __expf(-x)); }
; __device__ __forceinline__ void ret_out_unit(int b, int h, int c, LAS unsigned char* lds, const bf16_t* PROJ, const float* KV, bf16_t* H, int tid) {
;     ...
;     for (int cb = 0; cb < 8; ++cb) { const u32x2 gw = *(const u32x2*)(PROJ + qrow * EIN + 3072 + h * 128 + 16 * cb + 4 * fq);
;         const float g0 = silu_f(bflo(gw.x)), g1 = silu_f(bfhi(gw.x)), g2 = silu_f(bflo(gw.y)), g3 = silu_f(bfhi(gw.y));
;         u32x2 w; w.x = pk_bf16(o1[cb][0] * rinv * g0, o1[cb][1] * rinv * g1); w.y = pk_bf16(o1[cb][2] * rinv * g2, o1[cb][3] * rinv * g3);
;         *(u32x2*)(H + qrow * DM + h * 128 + 16 * cb + 4 * fq) = w; }
	v_lshlrev_b32_e32 v34, 16, v32
	v_mul_f32_e32 v35, 0xbfb8aa3b, v34
	v_exp_f32_e32 v35, v35
	v_and_b32_e32 v32, 0xffff0000, v32
	v_add_f32_e32 v35, 1.0, v35
	v_rcp_f32_e32 v37, v35
	s_nop 0
	v_mul_f32_e32 v34, v34, v37
	v_mul_f32_e32 v35, 0xbfb8aa3b, v32
	v_exp_f32_e32 v35, v35
	v_mul_f32_e32 v30, v34, v30
	v_add_f32_e32 v35, 1.0, v35
	v_rcp_f32_e32 v37, v35
	s_nop 0
	v_mul_f32_e32 v32, v32, v37
	v_lshlrev_b32_e32 v35, 16, v33
	v_mul_f32_e32 v36, 0xbfb8aa3b, v35
	v_exp_f32_e32 v36, v36
	v_and_b32_e32 v33, 0xffff0000, v33
	v_mul_f32_e32 v31, v32, v31
	v_cvt_pk_bf16_f32 v30, v30, v31
	v_add_f32_e32 v36, 1.0, v36
	v_rcp_f32_e32 v39, v36
	s_nop 0
	v_mul_f32_e32 v35, v35, v39
	v_mul_f32_e32 v36, 0xbfb8aa3b, v33
	v_exp_f32_e32 v36, v36
	v_mul_f32_e32 v28, v35, v28
	v_add_f32_e32 v36, 1.0, v36
	v_rcp_f32_e32 v39, v36
	s_nop 0
	v_mul_f32_e32 v33, v33, v39
	v_mul_f32_e32 v29, v33, v29
	v_cvt_pk_bf16_f32 v31, v28, v29
	global_load_dwordx2 v[28:29], v[4:5], off offset:64
	s_nop 0
	global_store_dwordx2 v[6:7], v[30:31], off offset:32
	s_waitcnt vmcnt(1)
	v_lshlrev_b32_e32 v30, 16, v28
	v_mul_f32_e32 v31, 0xbfb8aa3b, v30
	v_exp_f32_e32 v31, v31
	v_and_b32_e32 v28, 0xffff0000, v28
	v_add_f32_e32 v31, 1.0, v31
	v_rcp_f32_e32 v33, v31
	s_nop 0
	v_mul_f32_e32 v30, v30, v33
	v_mul_f32_e32 v31, 0xbfb8aa3b, v28
	v_exp_f32_e32 v31, v31
	v_mul_f32_e32 v26, v26, v30
	v_add_f32_e32 v31, 1.0, v31
	v_rcp_f32_e32 v33, v31
	s_nop 0
	v_mul_f32_e32 v28, v28, v33
	v_lshlrev_b32_e32 v31, 16, v29
	v_mul_f32_e32 v32, 0xbfb8aa3b, v31
	v_exp_f32_e32 v32, v32
	v_and_b32_e32 v29, 0xffff0000, v29
	v_mul_f32_e32 v27, v27, v28
	v_cvt_pk_bf16_f32 v26, v26, v27
	v_add_f32_e32 v32, 1.0, v32
	v_rcp_f32_e32 v34, v32
	s_nop 0
	v_mul_f32_e32 v31, v31, v34
	v_mul_f32_e32 v32, 0xbfb8aa3b, v29
	v_exp_f32_e32 v32, v32
	v_mul_f32_e32 v24, v24, v31
	v_add_f32_e32 v32, 1.0, v32
	v_rcp_f32_e32 v34, v32
	s_nop 0
	v_mul_f32_e32 v29, v29, v34
	v_mul_f32_e32 v25, v25, v29
	v_cvt_pk_bf16_f32 v27, v24, v25
	global_load_dwordx2 v[24:25], v[4:5], off offset:96
	s_nop 0
	global_store_dwordx2 v[6:7], v[26:27], off offset:64
	s_waitcnt vmcnt(1)
	v_lshlrev_b32_e32 v26, 16, v24
	v_mul_f32_e32 v27, 0xbfb8aa3b, v26
	v_exp_f32_e32 v27, v27
	v_and_b32_e32 v24, 0xffff0000, v24
	v_add_f32_e32 v27, 1.0, v27
	v_rcp_f32_e32 v29, v27
	s_nop 0
	v_mul_f32_e32 v26, v26, v29
	v_mul_f32_e32 v27, 0xbfb8aa3b, v24
	v_exp_f32_e32 v27, v27
	v_mul_f32_e32 v22, v22, v26
	v_add_f32_e32 v27, 1.0, v27
	v_rcp_f32_e32 v29, v27
	s_nop 0
	v_mul_f32_e32 v24, v24, v29
	v_lshlrev_b32_e32 v27, 16, v25
	v_mul_f32_e32 v28, 0xbfb8aa3b, v27
	v_exp_f32_e32 v28, v28
	v_and_b32_e32 v25, 0xffff0000, v25
	v_mul_f32_e32 v23, v23, v24
	v_cvt_pk_bf16_f32 v22, v22, v23
	v_add_f32_e32 v28, 1.0, v28
	v_rcp_f32_e32 v30, v28
	s_nop 0
	v_mul_f32_e32 v27, v27, v30
	v_mul_f32_e32 v28, 0xbfb8aa3b, v25
	v_exp_f32_e32 v28, v28
	v_mul_f32_e32 v20, v20, v27
	v_add_f32_e32 v28, 1.0, v28
	v_rcp_f32_e32 v30, v28
	s_nop 0
	v_mul_f32_e32 v25, v25, v30
	v_mul_f32_e32 v21, v21, v25
	v_cvt_pk_bf16_f32 v23, v20, v21
	global_load_dwordx2 v[20:21], v[4:5], off offset:128
	s_nop 0
	global_store_dwordx2 v[6:7], v[22:23], off offset:96
	s_waitcnt vmcnt(1)
; __device__ __forceinline__ unsigned pk_bf16(float lo, float hi) { unsigned r; asm volatile("v_cvt_pk_bf16_f32 %0, %1, %2" : "=v"(r) : "v"(lo), "v"(hi)); return r; }
; __device__ __forceinline__ float bflo(unsigned w) { return __uint_as_float(w << 16); }
; __device__ __forceinline__ float bfhi(unsigned w) { return __uint_as_float(w & 0xffff0000u); }
; __device__ __forceinline__ float silu_f(float x) { return x / (1.0f + __expf(-x)); }
; __device__ __forceinline__ void ret_out_unit(int b, int h, int c, LAS unsigned char* lds, const bf16_t* PROJ, const float* KV, bf16_t* H, int tid) {
;     ...
;     for (int cb = 0; cb < 8; ++cb) { const u32x2 gw = *(const u32x2*)(PROJ + qrow * EIN + 3072 + h * 128 + 16 * cb + 4 * fq);
;         const float g0 = silu_f(bflo(gw.x)), g1 = silu_f(bfhi(gw.x)), g2 = silu_f(bflo(gw.y)), g3 = silu_f(bfhi(gw.y));
;         u32x2 w; w.x = pk_bf16(o1[cb][0] * rinv * g0, o1[cb][1] * rinv * g1); w.y = pk_bf16(o1[cb][2] * rinv * g2, o1[cb][3] * rinv * g3);
;         *(u32x2*)(H + qrow * DM + h * 128 + 16 * cb + 4 * fq) = w; }
;     __syncthreads();
	v_lshlrev_b32_e32 v22, 16, v20
	v_mul_f32_e32 v23, 0xbfb8aa3b, v22
	v_exp_f32_e32 v23, v23
	v_and_b32_e32 v20, 0xffff0000, v20
	v_add_f32_e32 v23, 1.0, v23
	v_rcp_f32_e32 v25, v23
	s_nop 0
	v_mul_f32_e32 v22, v22, v25
	v_mul_f32_e32 v23, 0xbfb8aa3b, v20
	v_exp_f32_e32 v23, v23
	v_mul_f32_e32 v18, v18, v22
	v_add_f32_e32 v23, 1.0, v23
	v_rcp_f32_e32 v25, v23
	s_nop 0
	v_mul_f32_e32 v20, v20, v25
	v_lshlrev_b32_e32 v23, 16, v21
	v_mul_f32_e32 v24, 0xbfb8aa3b, v23
	v_exp_f32_e32 v24, v24
	v_and_b32_e32 v21, 0xffff0000, v21
	v_mul_f32_e32 v19, v19, v20
	v_cvt_pk_bf16_f32 v18, v18, v19
	v_add_f32_e32 v24, 1.0, v24
	v_rcp_f32_e32 v26, v24
	s_nop 0
	v_mul_f32_e32 v23, v23, v26
	v_mul_f32_e32 v24, 0xbfb8aa3b, v21
	v_exp_f32_e32 v24, v24
	v_mul_f32_e32 v16, v16, v23
	v_add_f32_e32 v24, 1.0, v24
	v_rcp_f32_e32 v26, v24
	s_nop 0
	v_mul_f32_e32 v21, v21, v26
	v_mul_f32_e32 v17, v17, v21
	v_cvt_pk_bf16_f32 v19, v16, v17
	global_load_dwordx2 v[16:17], v[4:5], off offset:160
	s_nop 0
	global_store_dwordx2 v[6:7], v[18:19], off offset:128
	s_waitcnt vmcnt(1)
	v_lshlrev_b32_e32 v18, 16, v16
	v_mul_f32_e32 v19, 0xbfb8aa3b, v18
	v_exp_f32_e32 v19, v19
	v_and_b32_e32 v16, 0xffff0000, v16
	v_add_f32_e32 v19, 1.0, v19
	v_rcp_f32_e32 v21, v19
	s_nop 0
	v_mul_f32_e32 v18, v18, v21
	v_mul_f32_e32 v19, 0xbfb8aa3b, v16
	v_exp_f32_e32 v19, v19
	v_mul_f32_e32 v14, v14, v18
	v_add_f32_e32 v19, 1.0, v19
	v_rcp_f32_e32 v21, v19
	s_nop 0
	v_mul_f32_e32 v16, v16, v21
	v_lshlrev_b32_e32 v19, 16, v17
	v_mul_f32_e32 v20, 0xbfb8aa3b, v19
	v_exp_f32_e32 v20, v20
	v_and_b32_e32 v17, 0xffff0000, v17
	v_mul_f32_e32 v15, v15, v16
	v_cvt_pk_bf16_f32 v14, v14, v15
	v_add_f32_e32 v20, 1.0, v20
	v_rcp_f32_e32 v22, v20
	s_nop 0
	v_mul_f32_e32 v19, v19, v22
	v_mul_f32_e32 v20, 0xbfb8aa3b, v17
	v_exp_f32_e32 v20, v20
	v_mul_f32_e32 v12, v12, v19
	v_add_f32_e32 v20, 1.0, v20
	v_rcp_f32_e32 v22, v20
	s_nop 0
	v_mul_f32_e32 v17, v17, v22
	v_mul_f32_e32 v13, v13, v17
	v_cvt_pk_bf16_f32 v15, v12, v13
	global_load_dwordx2 v[12:13], v[4:5], off offset:192
	s_nop 0
	global_store_dwordx2 v[6:7], v[14:15], off offset:160
	s_waitcnt vmcnt(1)
	v_lshlrev_b32_e32 v14, 16, v12
	v_mul_f32_e32 v15, 0xbfb8aa3b, v14
	v_exp_f32_e32 v15, v15
	v_and_b32_e32 v12, 0xffff0000, v12
	v_add_f32_e32 v15, 1.0, v15
	v_rcp_f32_e32 v17, v15
	s_nop 0
	v_mul_f32_e32 v14, v14, v17
	v_mul_f32_e32 v15, 0xbfb8aa3b, v12
	v_exp_f32_e32 v15, v15
	v_mul_f32_e32 v10, v10, v14
	v_add_f32_e32 v15, 1.0, v15
	v_rcp_f32_e32 v17, v15
	s_nop 0
	v_mul_f32_e32 v15, v12, v17
	v_lshlrev_b32_e32 v12, 16, v13
	v_mul_f32_e32 v16, 0xbfb8aa3b, v12
	v_exp_f32_e32 v16, v16
	v_mul_f32_e32 v11, v11, v15
	v_cvt_pk_bf16_f32 v10, v10, v11
	v_add_f32_e32 v16, 1.0, v16
	v_rcp_f32_e32 v18, v16
	s_nop 0
	v_mul_f32_e32 v16, v12, v18
	v_and_b32_e32 v12, 0xffff0000, v13
	v_mul_f32_e32 v13, 0xbfb8aa3b, v12
	v_exp_f32_e32 v13, v13
	v_mul_f32_e32 v8, v8, v16
	v_add_f32_e32 v13, 1.0, v13
	v_rcp_f32_e32 v18, v13
	s_nop 0
	v_mul_f32_e32 v12, v12, v18
	v_mul_f32_e32 v9, v9, v12
	v_cvt_pk_bf16_f32 v11, v8, v9
	global_load_dwordx2 v[4:5], v[4:5], off offset:224
	s_waitcnt vmcnt(0)
	v_lshlrev_b32_e32 v8, 16, v4
	v_mul_f32_e32 v9, 0xbfb8aa3b, v8
	v_exp_f32_e32 v9, v9
	global_store_dwordx2 v[6:7], v[10:11], off offset:192
	v_and_b32_e32 v4, 0xffff0000, v4
	v_add_f32_e32 v9, 1.0, v9
	v_rcp_f32_e32 v11, v9
	s_nop 0
	v_mul_f32_e32 v8, v8, v11
	v_mul_f32_e32 v9, 0xbfb8aa3b, v4
	v_exp_f32_e32 v9, v9
	v_mul_f32_e32 v2, v2, v8
	v_add_f32_e32 v9, 1.0, v9
	v_rcp_f32_e32 v11, v9
	s_nop 0
	v_mul_f32_e32 v4, v4, v11
	v_lshlrev_b32_e32 v9, 16, v5
	v_mul_f32_e32 v10, 0xbfb8aa3b, v9
	v_exp_f32_e32 v10, v10
	v_and_b32_e32 v5, 0xffff0000, v5
	v_mul_f32_e32 v3, v3, v4
	v_cvt_pk_bf16_f32 v2, v2, v3
	v_add_f32_e32 v10, 1.0, v10
	v_rcp_f32_e32 v12, v10
	s_nop 0
	v_mul_f32_e32 v9, v9, v12
	v_mul_f32_e32 v10, 0xbfb8aa3b, v5
	v_exp_f32_e32 v10, v10
	v_mul_f32_e32 v0, v0, v9
	v_add_f32_e32 v10, 1.0, v10
	v_rcp_f32_e32 v12, v10
	s_nop 0
	v_mul_f32_e32 v5, v5, v12
	v_mul_f32_e32 v1, v1, v5
	v_cvt_pk_bf16_f32 v3, v0, v1
	global_store_dwordx2 v[6:7], v[2:3], off offset:224
	s_barrier
	s_cbranch_scc0 .LBB0_418
